# static s_setprio 1 for waves 4-7 inside the diff/retention mixer loops (timing only)
# speedup vs baseline: 1.0082x; 1.0027x over previous
; __device__ __forceinline__ void wg_ret_task(ParamsCP pp, int layer, LAS unsigned char* lds, int b, int h, int qb, int tid_in) {
;     ...
;     const float lgf = log1pf(-exp2f(-pp->in[4][layer * 8 + h])) * LOG2E, lgb = log1pf(-exp2f(-pp->in[5][layer * 8 + h])) * LOG2E;
.LBB0_403:
	s_or_b64 exec, exec, s[14:15]
	v_add_f32_e32 v36, -1.0, v35
	v_sub_f32_e32 v37, v36, v35
	v_add_f32_e32 v37, 1.0, v37
	v_sub_f32_e64 v36, -v33, v36
	v_add_f32_e32 v39, v36, v37
	v_cvt_f64_f32_e32 v[36:37], v35
	v_frexp_exp_i32_f64_e32 v36, v[36:37]
	v_subbrev_co_u32_e64 v36, s[12:13], 0, v36, s[12:13]
	v_sub_u32_e32 v37, 0, v36
	v_ldexp_f32 v35, v35, v37
	v_ldexp_f32 v37, v39, v37
	v_add_f32_e32 v39, -1.0, v35
	v_add_f32_e32 v42, 1.0, v35
	v_add_f32_e32 v40, 1.0, v39
	v_add_f32_e32 v43, -1.0, v42
	v_sub_f32_e32 v40, v35, v40
	v_sub_f32_e32 v35, v35, v43
	v_add_f32_e32 v35, v37, v35
	v_add_f32_e32 v40, v37, v40
	v_add_f32_e32 v37, v42, v35
	v_rcp_f32_e32 v43, v37
	v_add_f32_e32 v41, v39, v40
	v_sub_f32_e32 v39, v41, v39
	v_sub_f32_e32 v39, v40, v39
	v_sub_f32_e32 v40, v37, v42
	v_sub_f32_e32 v35, v35, v40
	v_mul_f32_e32 v40, v41, v43
	v_mul_f32_e32 v42, v37, v40
	v_fma_f32 v44, v40, v37, -v42
	v_fmac_f32_e32 v44, v40, v35
	v_add_f32_e32 v45, v42, v44
	v_sub_f32_e32 v46, v41, v45
	v_sub_f32_e32 v41, v41, v46
	v_sub_f32_e32 v42, v45, v42
	v_sub_f32_e32 v41, v41, v45
	v_add_f32_e32 v39, v39, v41
	v_sub_f32_e32 v41, v42, v44
	v_add_f32_e32 v39, v41, v39
	v_add_f32_e32 v41, v46, v39
	v_mul_f32_e32 v42, v43, v41
	v_mul_f32_e32 v44, v37, v42
	v_fma_f32 v37, v42, v37, -v44
	v_fmac_f32_e32 v37, v42, v35
	v_sub_f32_e32 v35, v46, v41
	v_add_f32_e32 v35, v39, v35
	v_add_f32_e32 v39, v44, v37
	v_sub_f32_e32 v45, v41, v39
	v_sub_f32_e32 v41, v41, v45
	v_sub_f32_e32 v44, v39, v44
	v_sub_f32_e32 v39, v41, v39
	v_add_f32_e32 v35, v35, v39
	v_sub_f32_e32 v37, v44, v37
	v_cvt_f32_i32_e32 v36, v36
	v_add_f32_e32 v35, v37, v35
	v_add_f32_e32 v37, v40, v42
	v_add_f32_e32 v35, v45, v35
	v_sub_f32_e32 v39, v37, v40
	v_mul_f32_e32 v35, v43, v35
	v_sub_f32_e32 v39, v42, v39
	v_add_f32_e32 v35, v39, v35
	v_mul_f32_e32 v42, 0x3f317218, v36
	s_mov_b32 s12, 0x3f317218
	v_add_f32_e32 v39, v37, v35
	v_fma_f32 v43, v36, s12, -v42
	v_fmac_f32_e32 v43, 0xb102e308, v36
	v_sub_f32_e32 v36, v39, v37
	v_sub_f32_e32 v35, v35, v36
	v_add_f32_e32 v36, -1.0, v34
	v_sub_f32_e32 v37, v36, v34
	v_add_f32_e32 v37, 1.0, v37
	v_sub_f32_e64 v36, -v29, v36
	v_add_f32_e32 v47, v36, v37
	v_cvt_f64_f32_e32 v[36:37], v34
	v_frexp_exp_i32_f64_e32 v36, v[36:37]
	v_subbrev_co_u32_e32 v36, vcc, 0, v36, vcc
	v_sub_u32_e32 v37, 0, v36
	v_ldexp_f32 v34, v34, v37
	v_ldexp_f32 v37, v47, v37
	v_add_f32_e32 v47, -1.0, v34
	v_add_f32_e32 v50, 1.0, v34
	v_add_f32_e32 v48, 1.0, v47
	v_add_f32_e32 v51, -1.0, v50
	v_sub_f32_e32 v48, v34, v48
	v_sub_f32_e32 v34, v34, v51
	v_add_f32_e32 v34, v37, v34
	v_add_f32_e32 v48, v37, v48
	v_add_f32_e32 v37, v50, v34
	v_rcp_f32_e32 v51, v37
	v_add_f32_e32 v49, v47, v48
	v_sub_f32_e32 v47, v49, v47
	v_sub_f32_e32 v47, v48, v47
	v_sub_f32_e32 v48, v37, v50
	v_sub_f32_e32 v34, v34, v48
	v_mul_f32_e32 v48, v49, v51
	v_mul_f32_e32 v50, v37, v48
	v_fma_f32 v52, v48, v37, -v50
	v_fmac_f32_e32 v52, v48, v34
	v_add_f32_e32 v53, v50, v52
	v_sub_f32_e32 v54, v49, v53
	v_sub_f32_e32 v49, v49, v54
	v_sub_f32_e32 v50, v53, v50
	v_sub_f32_e32 v49, v49, v53
	v_add_f32_e32 v47, v47, v49
	v_sub_f32_e32 v49, v50, v52
	v_add_f32_e32 v47, v49, v47
	v_add_f32_e32 v49, v54, v47
	v_mul_f32_e32 v50, v51, v49
	v_mul_f32_e32 v40, v39, v39
	v_mov_b32_e32 v55, 0x3ecc95a3
	v_mul_f32_e32 v52, v37, v50
	v_fmamk_f32 v41, v40, 0x3e9b6dac, v55
	v_fma_f32 v37, v50, v37, -v52
	v_fmaak_f32 v41, v40, v41, 0x3f2aaada
	v_ldexp_f32 v44, v39, 1
	v_fmac_f32_e32 v37, v50, v34
	v_sub_f32_e32 v34, v54, v49
	v_mul_f32_e32 v39, v39, v40
	v_add_f32_e32 v34, v47, v34
	v_add_f32_e32 v47, v52, v37
	v_mul_f32_e32 v39, v39, v41
	v_sub_f32_e32 v53, v49, v47
	v_add_f32_e32 v40, v44, v39
	v_sub_f32_e32 v49, v49, v53
	v_sub_f32_e32 v41, v40, v44
	v_ldexp_f32 v35, v35, 1
	v_sub_f32_e32 v52, v47, v52
	v_sub_f32_e32 v47, v49, v47
	v_sub_f32_e32 v39, v39, v41
	v_add_f32_e32 v34, v34, v47
	v_sub_f32_e32 v37, v52, v37
	v_add_f32_e32 v35, v35, v39
	v_add_f32_e32 v34, v37, v34
	v_add_f32_e32 v39, v40, v35
	v_add_f32_e32 v34, v53, v34
	v_add_f32_e32 v53, v42, v43
	v_sub_f32_e32 v40, v39, v40
	v_sub_f32_e32 v35, v35, v40
	v_add_f32_e32 v40, v53, v39
	v_sub_f32_e32 v42, v53, v42
	v_sub_f32_e32 v41, v40, v53
	v_add_f32_e32 v37, v48, v50
	v_sub_f32_e32 v42, v43, v42
	v_sub_f32_e32 v43, v40, v41
	v_sub_f32_e32 v47, v37, v48
	v_cvt_f32_i32_e32 v36, v36
	v_sub_f32_e32 v43, v53, v43
	v_sub_f32_e32 v39, v39, v41
	v_mul_f32_e32 v34, v51, v34
	v_sub_f32_e32 v47, v50, v47
	v_add_f32_e32 v39, v39, v43
	v_add_f32_e32 v41, v42, v35
	v_add_f32_e32 v34, v47, v34
	v_sub_f32_e32 v43, v41, v42
	v_add_f32_e32 v39, v41, v39
; #define RT_COMMIT(KR, VR, buf) do { LAS unsigned char* bb_ = lds + (buf) * MX_BUF; \
;         if (kcopy) *(LAS u32x4*)(bb_ + krow * KP + kch * 16) = KR; *(LAS u32x4*)(bb_ + MX_KBYTES + vr * VP + vc * 16) = VR; } while (0)
; __device__ __forceinline__ void wg_ret_task(ParamsCP pp, int layer, LAS unsigned char* lds, int b, int h, int qb, int tid_in) {
;     ...
;     const float lgf = log1pf(-exp2f(-pp->in[4][layer * 8 + h])) * LOG2E, lgb = log1pf(-exp2f(-pp->in[5][layer * 8 + h])) * LOG2E;
;     const int tqA = 16 * jA + c16, tqB = 16 * jB + c16;
;     bf16x8 qA[2], qB[2];
;     { const bf16_t* qp = PROJ + (size_t)(qrowA + c16) * PP + qcol + 8 * quad; qA[0] = *(const bf16x8*)qp; qA[1] = *(const bf16x8*)(qp + 32);
;       const bf16_t* qp2 = PROJ + (size_t)(qrowB + c16) * PP + qcol + 8 * quad; qB[0] = *(const bf16x8*)qp2; qB[1] = *(const bf16x8*)(qp2 + 32); }
;     f32x4 accA[8], accB[8];
; #pragma unroll
;     for (int e0 = 0; e0 < 8; ++e0) { accA[e0] = (f32x4){0.f, 0.f, 0.f, 0.f}; accB[e0] = (f32x4){0.f, 0.f, 0.f, 0.f}; }
;     u32x4 kr0s = (u32x4){0u, 0u, 0u, 0u}, vr0s = kr0s, kr1s = kr0s, vr1s = kr0s;
;     ...
;     __syncthreads();
;     RT_ISSUE(kr0s, vr0s, 0); RT_COMMIT(kr0s, vr0s, 0); RT_ISSUE(kr1s, vr1s, 1);
;     __syncthreads();
	v_add_f32_e32 v47, v37, v34
	v_sub_f32_e32 v44, v41, v43
	v_add_f32_e32 v41, v40, v39
	v_mul_f32_e32 v48, v47, v47
	v_mul_f32_e32 v50, 0x3f317218, v36
	v_sub_f32_e32 v42, v42, v44
	v_sub_f32_e32 v35, v35, v43
	v_sub_f32_e32 v40, v41, v40
	v_fmamk_f32 v49, v48, 0x3e9b6dac, v55
	v_fma_f32 v51, v36, s12, -v50
	v_add_f32_e32 v35, v35, v42
	v_sub_f32_e32 v39, v39, v40
	v_fmaak_f32 v49, v48, v49, 0x3f2aaada
	v_fmac_f32_e32 v51, 0xb102e308, v36
	v_sub_f32_e32 v36, v47, v37
	v_add_f32_e32 v35, v35, v39
	v_mul_f32_e32 v39, v47, v48
	v_sub_f32_e32 v34, v34, v36
	v_ldexp_f32 v36, v47, 1
	v_mul_f32_e32 v39, v39, v49
	v_add_f32_e32 v40, v36, v39
	v_sub_f32_e32 v36, v40, v36
	v_ldexp_f32 v34, v34, 1
	v_sub_f32_e32 v36, v39, v36
	v_add_f32_e32 v35, v41, v35
	v_cmp_nlt_f32_e32 vcc, 1.0, v33
	v_add_f32_e32 v34, v34, v36
	v_add_f32_e32 v36, v40, v34
	v_cndmask_b32_e32 v35, v238, v35, vcc
	v_cmp_neq_f32_e32 vcc, 1.0, v33
	v_xor_b32_e32 v38, 0x80000000, v33
	v_and_b32_e32 v45, 0x7fffffff, v33
	v_cndmask_b32_e32 v33, v241, v35, vcc
	s_mov_b32 s13, 0x33800000
	v_add_f32_e32 v35, v50, v51
	v_sub_f32_e32 v39, v36, v40
	v_cmp_gt_f32_e32 vcc, s13, v45
	v_sub_f32_e32 v34, v34, v39
	v_add_f32_e32 v39, v35, v36
	v_cndmask_b32_e32 v33, v33, v38, vcc
	v_sub_f32_e32 v38, v35, v50
	v_sub_f32_e32 v40, v39, v35
	v_sub_f32_e32 v38, v51, v38
	v_sub_f32_e32 v41, v39, v40
	v_sub_f32_e32 v35, v35, v41
	v_sub_f32_e32 v36, v36, v40
	v_add_f32_e32 v40, v38, v34
	v_add_f32_e32 v36, v36, v35
	v_sub_f32_e32 v35, v40, v38
	v_sub_f32_e32 v41, v40, v35
	s_or_b32 s12, s64, 0x120
	v_sub_f32_e32 v38, v38, v41
	v_sub_f32_e32 v34, v34, v35
	v_add_f32_e32 v38, v34, v38
	v_mov_b32_e32 v34, s12
	v_mov_b32_e32 v35, s38
	v_cndmask_b32_e64 v34, v34, v35, s[10:11]
	v_or_b32_e32 v34, v34, v124
	v_mov_b32_e32 v35, v1
	v_lshl_add_u64 v[34:35], v[34:35], 1, v[118:119]
	global_load_dwordx4 v[92:95], v[34:35], off
	v_add_f32_e32 v34, v40, v36
	v_add_f32_e32 v35, v39, v34
	v_sub_f32_e32 v36, v35, v39
	v_sub_f32_e32 v34, v34, v36
	v_add_f32_e32 v34, v38, v34
	v_add_f32_e32 v34, v35, v34
	v_cmp_nlt_f32_e32 vcc, 1.0, v29
	v_and_b32_e32 v37, 0x7fffffff, v29
	v_xor_b32_e32 v46, 0x80000000, v29
	v_cndmask_b32_e32 v34, v238, v34, vcc
	v_cmp_neq_f32_e32 vcc, 1.0, v29
	v_lshl_add_u64 v[30:31], v[30:31], 1, s[84:85]
	s_movk_i32 s14, 0x90
	v_cndmask_b32_e32 v29, v241, v34, vcc
	v_cmp_gt_f32_e32 vcc, s13, v37
	v_lshl_add_u64 v[30:31], s[4:5], 1, v[30:31]
	s_mov_b64 s[4:5], 0x400
	v_cndmask_b32_e32 v29, v29, v46, vcc
	v_lshlrev_b32_e32 v52, 3, v32
	v_mul_f32_e32 v127, 0x3fb8aa3b, v29
	v_mad_u32_u24 v29, v122, s14, 0
	v_lshlrev_b32_e32 v117, 2, v32
	v_lshlrev_b32_e32 v32, 6, v122
	v_lshl_add_u64 v[120:121], v[30:31], 0, s[4:5]
	v_add_u32_e32 v30, s60, v122
	v_sub_u32_e32 v32, v29, v32
	v_sub_u32_e32 v130, 0, v30
	v_sub_u32_e32 v131, v30, v117
	v_lshl_or_b32 v30, s61, 4, v122
	v_mul_f32_e32 v126, 0x3fb8aa3b, v33
	v_sub_u32_e32 v132, 0, v30
	v_sub_u32_e32 v133, v30, v117
	v_mov_b32_e32 v72, 0
	v_add_u32_e32 v134, v29, v28
	v_add_u32_e32 v135, v32, v52
	v_mov_b64_e32 v[58:59], v[2:3]
	v_mov_b64_e32 v[54:55], v[2:3]
	v_mov_b64_e32 v[50:51], v[2:3]
	v_mov_b64_e32 v[46:47], v[2:3]
	v_mov_b64_e32 v[42:43], v[2:3]
	v_mov_b64_e32 v[38:39], v[2:3]
	v_mov_b64_e32 v[34:35], v[2:3]
	v_mov_b64_e32 v[30:31], v[2:3]
	s_mov_b32 s38, 4
	v_subrev_co_u32_e64 v128, s[12:13], 16, v123
	v_mad_u32_u24 v129, v123, s14, 0
	s_or_b32 s39, s64, 0x150
	s_mov_b32 s60, 0
	v_mov_b64_e32 v[56:57], v[0:1]
	v_mov_b64_e32 v[52:53], v[0:1]
	v_mov_b64_e32 v[48:49], v[0:1]
	v_mov_b64_e32 v[44:45], v[0:1]
	v_mov_b64_e32 v[40:41], v[0:1]
	v_mov_b64_e32 v[36:37], v[0:1]
	v_mov_b64_e32 v[32:33], v[0:1]
	v_mov_b64_e32 v[28:29], v[0:1]
	s_mov_b32 s61, 0
	v_mov_b32_e32 v73, v72
	v_mov_b32_e32 v74, v72
	v_mov_b32_e32 v75, v72
	v_mov_b32_e32 v88, v72
	v_mov_b32_e32 v89, v72
	v_mov_b32_e32 v90, v72
	v_mov_b32_e32 v91, v72
	v_mov_b32_e32 v84, v72
	v_mov_b32_e32 v85, v72
	v_mov_b32_e32 v86, v72
	v_mov_b32_e32 v87, v72
	v_mov_b32_e32 v80, v72
	v_mov_b32_e32 v81, v72
	v_mov_b32_e32 v82, v72
	v_mov_b32_e32 v83, v72
	v_mov_b32_e32 v76, v72
	v_mov_b32_e32 v77, v72
	v_mov_b32_e32 v78, v72
	v_mov_b32_e32 v79, v72
	v_mov_b32_e32 v68, v72
	v_mov_b32_e32 v69, v72
	v_mov_b32_e32 v70, v72
	v_mov_b32_e32 v71, v72
	v_mov_b32_e32 v64, v72
	v_mov_b32_e32 v65, v72
	v_mov_b32_e32 v66, v72
	v_mov_b32_e32 v67, v72
	v_mov_b32_e32 v60, v72
	v_mov_b32_e32 v61, v72
	v_mov_b32_e32 v62, v72
	v_mov_b32_e32 v63, v72
	v_readfirstlane_b32 s4, v206
	s_nop 3
	s_bitcmp1_b32 s4, 8
	s_cbranch_scc0 .Lprio_r_skip
	s_setprio 1
.Lprio_r_skip:
	s_waitcnt lgkmcnt(0)
	s_barrier
	s_branch .LBB0_406

; __device__ __forceinline__ unsigned f2bf(float f) { return pk2(f, 0.f) & 0xffffu; }
; __device__ __forceinline__ void wg_ret_task(ParamsCP pp, int layer, LAS unsigned char* lds, int b, int h, int qb, int tid_in) {
;     ...
;     bf16_t* ro = (bf16_t*)(pp->ws + WS_BIG + BIG_RO);
;     if (actA) { bf16_t* yb = ro + (size_t)(qrowA + 4 * quad) * 1024 + h * 128 + c16;
; #pragma unroll
;         for (int e0 = 0; e0 < 8; ++e0)
; #pragma unroll
;             for (int r = 0; r < 4; ++r) yb[(size_t)r * 1024 + e0 * 16] = (bf16_t)f2bf(accA[e0][r]); }
;     if (actB) { bf16_t* yb = ro + (size_t)(qrowB + 4 * quad) * 1024 + h * 128 + c16;
; #pragma unroll
;         for (int e0 = 0; e0 < 8; ++e0)
; #pragma unroll
;             for (int r = 0; r < 4; ++r) yb[(size_t)r * 1024 + e0 * 16] = (bf16_t)f2bf(accB[e0][r]); }
.LBB0_431:
	s_setprio 0
	s_and_b64 vcc, exec, s[24:25]
	v_lshlrev_b32_e32 v0, 1, v122
	s_cbranch_vccz .LBB0_433
	v_add_u32_e32 v2, s41, v117
	v_ashrrev_i32_e32 v3, 31, v2
	v_lshlrev_b64 v[2:3], 11, v[2:3]
	v_lshl_add_u64 v[2:3], s[18:19], 0, v[2:3]
	s_ashr_i32 s49, s48, 31
	v_lshl_add_u64 v[2:3], s[48:49], 1, v[2:3]
	v_lshl_add_u64 v[2:3], v[2:3], 0, v[0:1]
	v_cvt_pk_bf16_f32 v4, v72, s0
	global_store_short v[2:3], v4, off
	v_cvt_pk_bf16_f32 v4, v73, s0
	s_movk_i32 s4, 0x1000
	global_store_short v[2:3], v4, off offset:2048
	v_add_co_u32_e32 v4, vcc, s4, v2
	v_cvt_pk_bf16_f32 v6, v74, s0
	s_nop 0
	v_addc_co_u32_e32 v5, vcc, 0, v3, vcc
	global_store_short v[4:5], v6, off
	v_cvt_pk_bf16_f32 v6, v75, s0
	global_store_short v[4:5], v6, off offset:2048
	v_cvt_pk_bf16_f32 v6, v88, s0
	global_store_short v[2:3], v6, off offset:32
	v_cvt_pk_bf16_f32 v6, v89, s0
	global_store_short v[2:3], v6, off offset:2080
	v_cvt_pk_bf16_f32 v6, v90, s0
	global_store_short v[4:5], v6, off offset:32
	v_cvt_pk_bf16_f32 v6, v91, s0
	global_store_short v[4:5], v6, off offset:2080
	v_cvt_pk_bf16_f32 v6, v84, s0
	global_store_short v[2:3], v6, off offset:64
	v_cvt_pk_bf16_f32 v6, v85, s0
	global_store_short v[2:3], v6, off offset:2112
	v_cvt_pk_bf16_f32 v6, v86, s0
	global_store_short v[4:5], v6, off offset:64
	v_cvt_pk_bf16_f32 v6, v87, s0
	global_store_short v[4:5], v6, off offset:2112
	v_cvt_pk_bf16_f32 v6, v80, s0
	global_store_short v[2:3], v6, off offset:96
	v_cvt_pk_bf16_f32 v6, v81, s0
	global_store_short v[2:3], v6, off offset:2144
	v_cvt_pk_bf16_f32 v6, v82, s0
	global_store_short v[4:5], v6, off offset:96
	v_cvt_pk_bf16_f32 v6, v83, s0
	global_store_short v[4:5], v6, off offset:2144
	v_cvt_pk_bf16_f32 v6, v76, s0
	global_store_short v[2:3], v6, off offset:128
	v_cvt_pk_bf16_f32 v6, v77, s0
	global_store_short v[2:3], v6, off offset:2176
	v_cvt_pk_bf16_f32 v6, v78, s0
	global_store_short v[4:5], v6, off offset:128
	v_cvt_pk_bf16_f32 v6, v79, s0
	global_store_short v[4:5], v6, off offset:2176
	v_cvt_pk_bf16_f32 v6, v68, s0
	global_store_short v[2:3], v6, off offset:160
	v_cvt_pk_bf16_f32 v6, v69, s0
	global_store_short v[2:3], v6, off offset:2208
	v_cvt_pk_bf16_f32 v6, v70, s0
	global_store_short v[4:5], v6, off offset:160
	v_cvt_pk_bf16_f32 v6, v71, s0
	global_store_short v[4:5], v6, off offset:2208
	v_cvt_pk_bf16_f32 v6, v64, s0
	global_store_short v[2:3], v6, off offset:192
	v_cvt_pk_bf16_f32 v6, v65, s0
	global_store_short v[2:3], v6, off offset:2240
	v_cvt_pk_bf16_f32 v6, v66, s0
	global_store_short v[4:5], v6, off offset:192
	v_cvt_pk_bf16_f32 v6, v67, s0
	global_store_short v[4:5], v6, off offset:2240
	v_cvt_pk_bf16_f32 v6, v60, s0
	global_store_short v[2:3], v6, off offset:224
	v_cvt_pk_bf16_f32 v6, v61, s0
	global_store_short v[2:3], v6, off offset:2272
	v_cvt_pk_bf16_f32 v2, v62, s0
	global_store_short v[4:5], v2, off offset:224
	v_cvt_pk_bf16_f32 v2, v63, s0
	global_store_short v[4:5], v2, off offset:2272

; __device__ __forceinline__ float uniform_f(float x) { return __uint_as_float((unsigned)__builtin_amdgcn_readfirstlane((int)__float_as_uint(x))); }
; #define DF_COMMIT(buf) do { LAS unsigned char* bb_ = lds + (buf) * DF_BUF; \
;         _Pragma("unroll") for (int i_ = 0; i_ < 2; ++i_) { const int id_ = tid + 512 * i_, kr_ = id_ >> 5, kc_ = id_ & 31, vr_ = id_ >> 2, vc_ = id_ & 3; \
;             *(LAS u32x4*)(bb_ + kr_ * DF_KP + kc_ * 16) = kreg[i_]; *(LAS u32x4*)(bb_ + DF_KBYTES + vr_ * VP + vc_ * 16) = vreg[i_]; } } while (0)
; __device__ __forceinline__ void wg_diff_task(ParamsCP pp, int layer, LAS unsigned char* lds, int b, int h, int qb, int tid_in) {
;     ...
;     const bf16_t* PROJ = (const bf16_t*)(pp->ws + WS_BIG + BIG_PROJ); const bf16_t* VT = (const bf16_t*)(pp->ws + WS_BIG + BIG_VT);
;     const int lane = tid & 63, wave = __builtin_amdgcn_readfirstlane(tid >> 6), c16 = lane & 15, quad = lane >> 4;
;     const size_t qcol = PBUF + h * 256, kcol = PBUF + 1024 + h * 256;
;     const int vrow0 = V_DIFF + h * 256;
;     const int jraw = qb * 8 + wave; const bool active = jraw < 129; const int jq = active ? jraw : 128;
;     const int qrow0 = tile_row(b, jq);
;     const float* misc = (const float*)(pp->ws + WS_MISC) + 16 * layer;
;     const float lam = uniform_f(misc[0]), cb = uniform_f(misc[1] * LOG2E), sc = 0.08838834764831845f * LOG2E;
;     bf16x8 qf0[4], qf1[4];
;     { const bf16_t* qp = PROJ + (size_t)(qrow0 + c16) * PP + qcol + 8 * quad;
; #pragma unroll
;         for (int ks = 0; ks < 4; ++ks) { qf0[ks] = *(const bf16x8*)(qp + 32 * ks); qf1[ks] = *(const bf16x8*)(qp + 128 + 32 * ks); } }
;     f32x4 acc0[16], acc1[16];
; #pragma unroll
;     for (int e0 = 0; e0 < 16; ++e0) { acc0[e0] = (f32x4){0.f, 0.f, 0.f, 0.f}; acc1[e0] = (f32x4){0.f, 0.f, 0.f, 0.f}; }
;     float ls0 = 0.f, ls1 = 0.f;
;     u32x4 kreg[2], vreg[2];
;     ...
;     __syncthreads();
;     DF_ISSUE(0); DF_COMMIT(0);
;     __syncthreads();
.LBB0_440:
	v_and_b32_e32 v207, 15, v2
	v_add_u32_e32 v4, s30, v207
	s_lshl_b32 s24, s10, 8
	v_ashrrev_i32_e32 v5, 31, v4
	s_ashr_i32 s25, s24, 31
	v_lshlrev_b64 v[4:5], 12, v[4:5]
	v_bfe_u32 v208, v2, 4, 2
	v_lshl_add_u64 v[4:5], s[84:85], 0, v[4:5]
	s_lshl_b64 s[4:5], s[24:25], 1
	v_lshl_add_u64 v[4:5], v[4:5], 0, s[4:5]
	v_lshlrev_b32_e32 v0, 4, v208
	v_lshl_add_u64 v[4:5], v[4:5], 0, v[0:1]
	s_mov_b64 s[10:11], 0x8100000
	s_add_i32 s38, s24, 0x400
	v_lshl_add_u64 v[6:7], v[4:5], 0, s[10:11]
	s_mov_b32 s10, 0x8100000
	s_bitset1_b32 s9, 8
	v_add_co_u32_e32 v4, vcc, s10, v4
	s_add_u32 s4, s84, s4
	v_lshlrev_b32_e32 v10, 4, v2
	v_addc_co_u32_e32 v5, vcc, 0, v5, vcc
	s_addc_u32 s5, s85, s5
	v_and_b32_e32 v180, 0x1f0, v10
	v_mov_b32_e32 v181, v1
	global_load_dwordx4 v[114:117], v[4:5], off
	global_load_dwordx2 v[178:179], v1, s[20:21]
	global_load_dwordx4 v[118:121], v[6:7], off offset:64
	global_load_dwordx4 v[122:125], v[6:7], off offset:256
	global_load_dwordx4 v[126:129], v[6:7], off offset:320
	global_load_dwordx4 v[134:137], v[6:7], off offset:128
	global_load_dwordx4 v[138:141], v[6:7], off offset:192
	global_load_dwordx4 v[142:145], v[6:7], off offset:384
	global_load_dwordx4 v[146:149], v[6:7], off offset:448
	v_and_b32_e32 v3, 2, v2
	v_lshl_add_u64 v[4:5], s[4:5], 0, v[180:181]
	s_mov_b64 s[4:5], 0x8100800
	v_lshlrev_b32_e32 v6, 3, v2
	v_lshl_add_u64 v[182:183], v[4:5], 0, s[4:5]
	v_mov_b32_e32 v4, s9
	v_mov_b32_e32 v11, s8
	v_cmp_eq_u32_e64 s[8:9], 0, v3
	v_and_b32_e32 v181, 8, v6
	v_ashrrev_i32_e32 v209, 5, v2
	v_cndmask_b32_e64 v3, v4, v11, s[8:9]
	v_or_b32_e32 v4, v3, v181
	v_mov_b32_e32 v3, s37
	v_cmp_gt_i32_e64 s[10:11], 16, v209
	v_ashrrev_i32_e32 v12, 2, v2
	v_add_u32_e32 v2, 0x200, v2
	v_cndmask_b32_e64 v6, v3, v11, s[10:11]
	v_add_u32_e32 v6, v6, v209
	v_ashrrev_i32_e32 v7, 31, v6
	v_ashrrev_i32_e32 v5, 31, v4
	v_lshlrev_b64 v[6:7], 12, v[6:7]
	v_ashrrev_i32_e32 v210, 5, v2
	v_lshl_add_u64 v[4:5], v[4:5], 1, s[16:17]
	v_lshl_add_u64 v[6:7], v[182:183], 0, v[6:7]
	v_add_u32_e32 v13, s38, v12
	s_mov_b32 s41, 0x10200
	v_cmp_gt_i32_e64 s[12:13], 16, v210
	s_waitcnt vmcnt(63) expcnt(7) lgkmcnt(15)
	s_barrier
	v_mad_i64_i32 v[8:9], s[4:5], v13, s41, v[4:5]
	global_load_dwordx4 v[162:165], v[6:7], off
	global_load_dwordx4 v[166:169], v[8:9], off
	v_ashrrev_i32_e32 v6, 2, v2
	v_cndmask_b32_e64 v2, v3, v11, s[12:13]
	v_add_u32_e32 v2, v2, v210
	v_ashrrev_i32_e32 v3, 31, v2
	v_lshlrev_b64 v[2:3], 12, v[2:3]
	v_lshl_add_u64 v[2:3], v[182:183], 0, v[2:3]
	v_add_u32_e32 v7, s38, v6
	global_load_dwordx4 v[170:173], v[2:3], off
	v_mad_i64_i32 v[2:3], s[4:5], v7, s41, v[4:5]
	global_load_dwordx4 v[174:177], v[2:3], off
	v_mad_i64_i32 v[184:185], s[4:5], v13, s41, 0
	v_mad_i64_i32 v[186:187], s[4:5], v7, s41, 0
	v_mov_b32_e32 v2, 0x3fb8aa3b
	s_movk_i32 s5, 0x210
	v_and_b32_e32 v212, 48, v10
	v_mul_lo_u32 v213, v209, s5
	s_movk_i32 s4, 0x50
	v_add_u32_e32 v3, 0, v212
	v_mul_lo_u32 v214, v12, s4
	v_mul_lo_u32 v215, v210, s5
	v_mul_lo_u32 v216, v6, s4
	v_mov_b32_e32 v22, 0
	s_mov_b32 s38, 3
	s_mov_b32 s39, 0
	v_lshlrev_b32_e32 v211, 3, v208
	v_mul_u32_u24_e32 v217, 0x210, v207
	v_mul_u32_u24_e32 v218, 0x50, v207
	v_mov_b32_e32 v23, v22
	v_mov_b32_e32 v24, v22
	v_mov_b32_e32 v25, v22
	v_mov_b32_e32 v50, v22
	v_mov_b32_e32 v51, v22
	v_mov_b32_e32 v52, v22
	v_mov_b32_e32 v53, v22
	v_mov_b32_e32 v58, v22
	v_mov_b32_e32 v59, v22
	s_waitcnt vmcnt(11)
	v_readfirstlane_b32 s40, v179
	v_mov_b32_e32 v60, v22
	v_mov_b32_e32 v61, v22
	v_mul_f32_e32 v179, s40, v2
	v_add_u32_e32 v2, 0, v180
	v_add_u32_e32 v4, v2, v213
	v_add_u32_e32 v2, v2, v215
	s_add_i32 s40, s37, 32
	v_mov_b32_e32 v70, v22
	v_mov_b32_e32 v71, v22
	v_mov_b32_e32 v72, v22
	v_mov_b32_e32 v73, v22
	v_mov_b32_e32 v82, v22
	v_mov_b32_e32 v83, v22
	v_mov_b32_e32 v84, v22
	v_mov_b32_e32 v85, v22
	v_mov_b32_e32 v90, v22
	v_mov_b32_e32 v91, v22
	v_mov_b32_e32 v92, v22
	v_mov_b32_e32 v93, v22
	v_mov_b32_e32 v102, v22
	v_mov_b32_e32 v103, v22
	v_mov_b32_e32 v104, v22
	v_mov_b32_e32 v105, v22
	v_mov_b32_e32 v130, v22
	v_mov_b32_e32 v131, v22
	v_mov_b32_e32 v132, v22
	v_mov_b32_e32 v133, v22
	v_mov_b32_e32 v42, v22
	v_mov_b32_e32 v43, v22
	v_mov_b32_e32 v44, v22
	v_mov_b32_e32 v45, v22
	v_mov_b32_e32 v34, v22
	v_mov_b32_e32 v35, v22
	v_mov_b32_e32 v36, v22
	v_mov_b32_e32 v37, v22
	v_mov_b32_e32 v26, v22
	v_mov_b32_e32 v27, v22
	v_mov_b32_e32 v28, v22
	s_waitcnt vmcnt(3)
	ds_write_b128 v4, v[162:165]
	v_add_u32_e32 v4, v3, v214
	s_waitcnt vmcnt(2)
	ds_write_b128 v4, v[166:169] offset:16896
	v_mov_b32_e32 v29, v22
	v_mov_b32_e32 v18, v22
	v_mov_b32_e32 v19, v22
	v_mov_b32_e32 v20, v22
	v_mov_b32_e32 v21, v22
	v_mov_b32_e32 v14, v22
	s_waitcnt vmcnt(1)
	ds_write_b128 v2, v[170:173]
	v_add_u32_e32 v2, v3, v216
	v_mov_b32_e32 v15, v22
	s_waitcnt vmcnt(0)
	ds_write_b128 v2, v[174:177] offset:16896
	v_mov_b32_e32 v16, v22
	v_mov_b32_e32 v17, v22
	v_mov_b32_e32 v10, v22
	v_mov_b32_e32 v11, v22
	v_mov_b32_e32 v12, v22
	v_mov_b32_e32 v13, v22
	v_mov_b32_e32 v6, v22
	v_mov_b32_e32 v7, v22
	v_mov_b32_e32 v8, v22
	v_mov_b32_e32 v9, v22
	v_mov_b32_e32 v2, v22
	v_mov_b32_e32 v3, v22
	v_mov_b32_e32 v4, v22
	v_mov_b32_e32 v5, v22
	v_mov_b32_e32 v158, v22
	v_mov_b32_e32 v159, v22
	v_mov_b32_e32 v160, v22
	v_mov_b32_e32 v161, v22
	v_mov_b32_e32 v154, v22
	v_mov_b32_e32 v155, v22
	v_mov_b32_e32 v156, v22
	v_mov_b32_e32 v157, v22
	v_mov_b32_e32 v150, v22
	v_mov_b32_e32 v151, v22
	v_mov_b32_e32 v152, v22
	v_mov_b32_e32 v153, v22
	v_mov_b32_e32 v110, v22
	v_mov_b32_e32 v111, v22
	v_mov_b32_e32 v112, v22
	v_mov_b32_e32 v113, v22
	v_mov_b32_e32 v106, v22
	v_mov_b32_e32 v107, v22
	v_mov_b32_e32 v108, v22
	v_mov_b32_e32 v109, v22
	v_mov_b32_e32 v98, v22
	v_mov_b32_e32 v99, v22
	v_mov_b32_e32 v100, v22
	v_mov_b32_e32 v101, v22
	v_mov_b32_e32 v94, v22
	v_mov_b32_e32 v95, v22
	v_mov_b32_e32 v96, v22
	v_mov_b32_e32 v97, v22
	v_mov_b32_e32 v86, v22
	v_mov_b32_e32 v87, v22
	v_mov_b32_e32 v88, v22
	v_mov_b32_e32 v89, v22
	v_mov_b32_e32 v78, v22
	v_mov_b32_e32 v79, v22
	v_mov_b32_e32 v80, v22
	v_mov_b32_e32 v81, v22
	v_mov_b32_e32 v74, v22
	v_mov_b32_e32 v75, v22
	v_mov_b32_e32 v76, v22
	v_mov_b32_e32 v77, v22
	v_mov_b32_e32 v66, v22
	v_mov_b32_e32 v67, v22
	v_mov_b32_e32 v68, v22
	v_mov_b32_e32 v69, v22
	v_mov_b32_e32 v62, v22
	v_mov_b32_e32 v63, v22
	v_mov_b32_e32 v64, v22
	v_mov_b32_e32 v65, v22
	v_mov_b32_e32 v54, v22
	v_mov_b32_e32 v55, v22
	v_mov_b32_e32 v56, v22
	v_mov_b32_e32 v57, v22
	v_mov_b32_e32 v46, v22
	v_mov_b32_e32 v47, v22
	v_mov_b32_e32 v48, v22
	v_mov_b32_e32 v49, v22
	v_mov_b32_e32 v38, v22
	v_mov_b32_e32 v39, v22
	v_mov_b32_e32 v40, v22
	v_mov_b32_e32 v41, v22
	v_mov_b32_e32 v30, v22
	v_mov_b32_e32 v31, v22
	v_mov_b32_e32 v32, v22
	v_mov_b32_e32 v33, v22
	v_mov_b32_e32 v188, v22
	v_mov_b32_e32 v189, v22
	v_readfirstlane_b32 s4, v206
	s_nop 3
	s_bitcmp1_b32 s4, 8
	s_cbranch_scc0 .Lprio_d_skip
	s_setprio 1

; __device__ __forceinline__ unsigned f2bf(float f) { return pk2(f, 0.f) & 0xffffu; }
; __device__ __forceinline__ float fast_rcp(float x) { return __builtin_amdgcn_rcpf(x); }
; __device__ __forceinline__ void wg_diff_task(ParamsCP pp, int layer, LAS unsigned char* lds, int b, int h, int qb, int tid_in) {
;     ...
;     ls0 += __shfl_xor(ls0, 16); ls0 += __shfl_xor(ls0, 32); ls1 += __shfl_xor(ls1, 16); ls1 += __shfl_xor(ls1, 32);
;     float i0[4], i1[4];
; #pragma unroll
;     for (int r = 0; r < 4; ++r) { i0[r] = fast_rcp(__shfl(ls0, 4 * quad + r)); i1[r] = lam * fast_rcp(__shfl(ls1, 4 * quad + r)); }
;     if (active) {
;         bf16_t* yb = (bf16_t*)(pp->ws + WS_BIG + BIG_PROJ) + PBUF + (size_t)(qrow0 + 4 * quad) * PP + h * 256 + c16;
; #pragma unroll
;         for (int e0 = 0; e0 < 16; ++e0)
; #pragma unroll
;             for (int r = 0; r < 4; ++r) yb[(size_t)r * PP + e0 * 16] = (bf16_t)f2bf(acc0[e0][r] * i0[r] - acc1[e0][r] * i1[r]);
.LBB0_446:
	s_setprio 0
	v_and_b32_e32 v114, 64, v239
	v_xor_b32_e32 v0, 16, v239
	v_add_u32_e32 v115, 64, v114
	v_cmp_lt_i32_e32 vcc, v0, v115
	v_xor_b32_e32 v117, 32, v239
	v_readfirstlane_b32 s4, v178
	v_cndmask_b32_e32 v0, v239, v0, vcc
	v_lshlrev_b32_e32 v0, 2, v0
	ds_bpermute_b32 v116, v0, v188
	ds_bpermute_b32 v0, v0, v189
	v_cmp_lt_i32_e32 vcc, v117, v115
	s_mov_b32 s50, 0x3b800000
	s_waitcnt lgkmcnt(1)
	v_add_f32_e32 v116, v188, v116
	v_cndmask_b32_e32 v115, v239, v117, vcc
	v_lshlrev_b32_e32 v115, 2, v115
	s_waitcnt lgkmcnt(0)
	v_add_f32_e32 v0, v189, v0
	ds_bpermute_b32 v117, v115, v116
	ds_bpermute_b32 v115, v115, v0
	s_and_b64 vcc, s[14:15], exec
	s_waitcnt lgkmcnt(1)
	v_add_f32_e32 v120, v116, v117
	s_waitcnt lgkmcnt(0)
	v_add_f32_e32 v121, v0, v115
	v_lshlrev_b32_e32 v0, 2, v208
	v_or_b32_e32 v114, v114, v0
	v_lshlrev_b32_e32 v122, 2, v114
	ds_bpermute_b32 v114, v122, v120
	ds_bpermute_b32 v116, v122, v121
	ds_bpermute_b32 v115, v122, v120 offset:4
	ds_bpermute_b32 v118, v122, v121 offset:4
	ds_bpermute_b32 v117, v122, v120 offset:8
	ds_bpermute_b32 v119, v122, v121 offset:8
	ds_bpermute_b32 v120, v122, v120 offset:12
	ds_bpermute_b32 v121, v122, v121 offset:12
	s_cbranch_vccz .LBB0_381
	s_waitcnt lgkmcnt(6)
	v_rcp_f32_e32 v116, v116
	v_rcp_f32_e32 v129, v114
	v_add_u32_e32 v114, s30, v0
	s_waitcnt lgkmcnt(5)
	v_rcp_f32_e32 v127, v115
	v_ashrrev_i32_e32 v115, 31, v114
	s_waitcnt lgkmcnt(0)
	v_rcp_f32_e32 v121, v121
	v_rcp_f32_e32 v119, v119
	v_rcp_f32_e32 v118, v118
	v_lshlrev_b64 v[114:115], 12, v[114:115]
	v_lshl_add_u64 v[114:115], s[22:23], 0, v[114:115]
	v_mul_f32_e32 v128, s4, v116
	v_lshl_add_u64 v[114:115], s[24:25], 1, v[114:115]
	v_lshlrev_b32_e32 v0, 1, v207
	v_lshl_add_u64 v[114:115], v[114:115], 0, v[0:1]
	v_mul_f32_e32 v0, v130, v128
	v_mul_f32_e32 v123, s4, v121
	v_mul_f32_e32 v124, s4, v119
	v_mul_f32_e32 v126, s4, v118
	v_fma_f32 v0, v158, v129, -v0
	s_movk_i32 s4, 0x1000
	v_cvt_pk_bf16_f32 v0, v0, s0
	v_add_co_u32_e32 v116, vcc, s4, v114
	v_rcp_f32_e32 v125, v117
	global_store_short v[114:115], v0, off
	v_mul_f32_e32 v0, v131, v126
	v_addc_co_u32_e32 v117, vcc, 0, v115, vcc
	s_movk_i32 s4, 0x2000
	v_fma_f32 v0, v159, v127, -v0
	v_add_co_u32_e32 v118, vcc, s4, v114
	v_cvt_pk_bf16_f32 v0, v0, s0
	s_nop 0
	v_addc_co_u32_e32 v119, vcc, 0, v115, vcc
	v_rcp_f32_e32 v122, v120
	global_store_short v[118:119], v0, off offset:-4096
	v_mul_f32_e32 v0, v132, v124
	v_fma_f32 v0, v160, v125, -v0
	v_cvt_pk_bf16_f32 v0, v0, s0
	global_store_short v[118:119], v0, off
	v_mul_f32_e32 v0, v133, v123
	s_movk_i32 s4, 0x3000
	v_fma_f32 v0, v161, v122, -v0
	v_add_co_u32_e32 v120, vcc, s4, v114
	v_cvt_pk_bf16_f32 v0, v0, s0
	s_nop 0
	v_addc_co_u32_e32 v121, vcc, 0, v115, vcc
	global_store_short v[120:121], v0, off
	v_mul_f32_e32 v0, v102, v128
	v_fma_f32 v0, v154, v129, -v0
	v_cvt_pk_bf16_f32 v0, v0, s0
	global_store_short v[114:115], v0, off offset:32
	v_mul_f32_e32 v0, v103, v126
	v_fma_f32 v0, v155, v127, -v0
	v_cvt_pk_bf16_f32 v0, v0, s0
	global_store_short v[116:117], v0, off offset:32
	v_mul_f32_e32 v0, v104, v124
	v_fma_f32 v0, v156, v125, -v0
	v_cvt_pk_bf16_f32 v0, v0, s0
	global_store_short v[118:119], v0, off offset:32
	v_mul_f32_e32 v0, v105, v123
	v_fma_f32 v0, v157, v122, -v0
	v_cvt_pk_bf16_f32 v0, v0, s0
	global_store_short v[120:121], v0, off offset:32
	v_mul_f32_e32 v0, v90, v128
	v_fma_f32 v0, v150, v129, -v0
	v_cvt_pk_bf16_f32 v0, v0, s0
	global_store_short v[114:115], v0, off offset:64
	v_mul_f32_e32 v0, v91, v126
	v_fma_f32 v0, v151, v127, -v0
	v_cvt_pk_bf16_f32 v0, v0, s0
	global_store_short v[116:117], v0, off offset:64
	v_mul_f32_e32 v0, v92, v124
	v_fma_f32 v0, v152, v125, -v0
	v_cvt_pk_bf16_f32 v0, v0, s0
	global_store_short v[118:119], v0, off offset:64
	v_mul_f32_e32 v0, v93, v123
	v_fma_f32 v0, v153, v122, -v0
	v_cvt_pk_bf16_f32 v0, v0, s0
	global_store_short v[120:121], v0, off offset:64
	v_mul_f32_e32 v0, v82, v128
	v_fma_f32 v0, v110, v129, -v0
	v_cvt_pk_bf16_f32 v0, v0, s0
	global_store_short v[114:115], v0, off offset:96
	v_mul_f32_e32 v0, v83, v126
	v_fma_f32 v0, v111, v127, -v0
	v_cvt_pk_bf16_f32 v0, v0, s0
	global_store_short v[116:117], v0, off offset:96
	v_mul_f32_e32 v0, v84, v124
	v_fma_f32 v0, v112, v125, -v0
	v_cvt_pk_bf16_f32 v0, v0, s0
	global_store_short v[118:119], v0, off offset:96
	v_mul_f32_e32 v0, v85, v123
	v_fma_f32 v0, v113, v122, -v0
	v_cvt_pk_bf16_f32 v0, v0, s0
	global_store_short v[120:121], v0, off offset:96
	v_mul_f32_e32 v0, v70, v128
	v_fma_f32 v0, v106, v129, -v0
	v_cvt_pk_bf16_f32 v0, v0, s0
	global_store_short v[114:115], v0, off offset:128
	v_mul_f32_e32 v0, v71, v126
	v_fma_f32 v0, v107, v127, -v0
	v_cvt_pk_bf16_f32 v0, v0, s0
	global_store_short v[116:117], v0, off offset:128
	v_mul_f32_e32 v0, v72, v124
	v_fma_f32 v0, v108, v125, -v0
	v_cvt_pk_bf16_f32 v0, v0, s0
	global_store_short v[118:119], v0, off offset:128
	v_mul_f32_e32 v0, v73, v123
	v_fma_f32 v0, v109, v122, -v0
	v_cvt_pk_bf16_f32 v0, v0, s0
	global_store_short v[120:121], v0, off offset:128
	v_mul_f32_e32 v0, v58, v128
	v_fma_f32 v0, v98, v129, -v0
	v_cvt_pk_bf16_f32 v0, v0, s0
	global_store_short v[114:115], v0, off offset:160
	v_mul_f32_e32 v0, v59, v126
	v_fma_f32 v0, v99, v127, -v0
	v_cvt_pk_bf16_f32 v0, v0, s0
	global_store_short v[116:117], v0, off offset:160
	v_mul_f32_e32 v0, v60, v124
	v_fma_f32 v0, v100, v125, -v0
	v_cvt_pk_bf16_f32 v0, v0, s0
	global_store_short v[118:119], v0, off offset:160
	v_mul_f32_e32 v0, v61, v123
	v_fma_f32 v0, v101, v122, -v0
	v_cvt_pk_bf16_f32 v0, v0, s0
	global_store_short v[120:121], v0, off offset:160
	v_mul_f32_e32 v0, v50, v128
; __device__ __forceinline__ unsigned f2bf(float f) { return pk2(f, 0.f) & 0xffffu; }
; __device__ __forceinline__ void wg_diff_task(ParamsCP pp, int layer, LAS unsigned char* lds, int b, int h, int qb, int tid_in) {
;     ...
;     if (active) {
;         bf16_t* yb = (bf16_t*)(pp->ws + WS_BIG + BIG_PROJ) + PBUF + (size_t)(qrow0 + 4 * quad) * PP + h * 256 + c16;
; #pragma unroll
;         for (int e0 = 0; e0 < 16; ++e0)
; #pragma unroll
;             for (int r = 0; r < 4; ++r) yb[(size_t)r * PP + e0 * 16] = (bf16_t)f2bf(acc0[e0][r] * i0[r] - acc1[e0][r] * i1[r]);
	v_fma_f32 v0, v94, v129, -v0
	v_cvt_pk_bf16_f32 v0, v0, s0
	global_store_short v[114:115], v0, off offset:192
	v_mul_f32_e32 v0, v51, v126
	v_fma_f32 v0, v95, v127, -v0
	v_cvt_pk_bf16_f32 v0, v0, s0
	global_store_short v[116:117], v0, off offset:192
	v_mul_f32_e32 v0, v52, v124
	v_fma_f32 v0, v96, v125, -v0
	v_cvt_pk_bf16_f32 v0, v0, s0
	global_store_short v[118:119], v0, off offset:192
	v_mul_f32_e32 v0, v53, v123
	v_fma_f32 v0, v97, v122, -v0
	v_cvt_pk_bf16_f32 v0, v0, s0
	global_store_short v[120:121], v0, off offset:192
	v_mul_f32_e32 v0, v22, v128
	v_fma_f32 v0, v86, v129, -v0
	v_cvt_pk_bf16_f32 v0, v0, s0
	global_store_short v[114:115], v0, off offset:224
	v_mul_f32_e32 v0, v23, v126
	v_fma_f32 v0, v87, v127, -v0
	v_cvt_pk_bf16_f32 v0, v0, s0
	global_store_short v[116:117], v0, off offset:224
	v_mul_f32_e32 v0, v24, v124
	v_fma_f32 v0, v88, v125, -v0
	v_cvt_pk_bf16_f32 v0, v0, s0
	global_store_short v[118:119], v0, off offset:224
	v_mul_f32_e32 v0, v25, v123
	v_fma_f32 v0, v89, v122, -v0
	v_cvt_pk_bf16_f32 v0, v0, s0
	global_store_short v[120:121], v0, off offset:224
	v_mul_f32_e32 v0, v42, v128
	v_fma_f32 v0, v78, v129, -v0
	v_cvt_pk_bf16_f32 v0, v0, s0
	global_store_short v[114:115], v0, off offset:256
	v_mul_f32_e32 v0, v43, v126
	v_fma_f32 v0, v79, v127, -v0
	v_cvt_pk_bf16_f32 v0, v0, s0
	global_store_short v[116:117], v0, off offset:256
	v_mul_f32_e32 v0, v44, v124
	v_fma_f32 v0, v80, v125, -v0
	v_cvt_pk_bf16_f32 v0, v0, s0
	global_store_short v[118:119], v0, off offset:256
	v_mul_f32_e32 v0, v45, v123
	v_fma_f32 v0, v81, v122, -v0
	v_cvt_pk_bf16_f32 v0, v0, s0
	global_store_short v[120:121], v0, off offset:256
	v_mul_f32_e32 v0, v34, v128
	v_fma_f32 v0, v74, v129, -v0
	v_cvt_pk_bf16_f32 v0, v0, s0
	global_store_short v[114:115], v0, off offset:288
	v_mul_f32_e32 v0, v35, v126
	v_fma_f32 v0, v75, v127, -v0
	v_cvt_pk_bf16_f32 v0, v0, s0
	global_store_short v[116:117], v0, off offset:288
	v_mul_f32_e32 v0, v36, v124
	v_fma_f32 v0, v76, v125, -v0
	v_cvt_pk_bf16_f32 v0, v0, s0
	global_store_short v[118:119], v0, off offset:288
	v_mul_f32_e32 v0, v37, v123
	v_fma_f32 v0, v77, v122, -v0
	v_cvt_pk_bf16_f32 v0, v0, s0
	global_store_short v[120:121], v0, off offset:288
	v_mul_f32_e32 v0, v26, v128
	v_fma_f32 v0, v66, v129, -v0
	v_cvt_pk_bf16_f32 v0, v0, s0
	global_store_short v[114:115], v0, off offset:320
	v_mul_f32_e32 v0, v27, v126
	v_fma_f32 v0, v67, v127, -v0
	v_cvt_pk_bf16_f32 v0, v0, s0
	global_store_short v[116:117], v0, off offset:320
	v_mul_f32_e32 v0, v28, v124
	v_fma_f32 v0, v68, v125, -v0
	v_cvt_pk_bf16_f32 v0, v0, s0
	global_store_short v[118:119], v0, off offset:320
	v_mul_f32_e32 v0, v29, v123
	v_fma_f32 v0, v69, v122, -v0
	v_cvt_pk_bf16_f32 v0, v0, s0
	global_store_short v[120:121], v0, off offset:320
	v_mul_f32_e32 v0, v18, v128
	v_fma_f32 v0, v62, v129, -v0
	v_cvt_pk_bf16_f32 v0, v0, s0
	global_store_short v[114:115], v0, off offset:352
	v_mul_f32_e32 v0, v19, v126
	v_fma_f32 v0, v63, v127, -v0
	v_cvt_pk_bf16_f32 v0, v0, s0
	global_store_short v[116:117], v0, off offset:352
	v_mul_f32_e32 v0, v20, v124
	v_fma_f32 v0, v64, v125, -v0
	v_cvt_pk_bf16_f32 v0, v0, s0
	global_store_short v[118:119], v0, off offset:352
	v_mul_f32_e32 v0, v21, v123
	v_fma_f32 v0, v65, v122, -v0
	v_cvt_pk_bf16_f32 v0, v0, s0
	global_store_short v[120:121], v0, off offset:352
	v_mul_f32_e32 v0, v14, v128
	v_fma_f32 v0, v54, v129, -v0
	v_cvt_pk_bf16_f32 v0, v0, s0
	global_store_short v[114:115], v0, off offset:384
	v_mul_f32_e32 v0, v15, v126
	v_fma_f32 v0, v55, v127, -v0
	v_cvt_pk_bf16_f32 v0, v0, s0
	global_store_short v[116:117], v0, off offset:384
	v_mul_f32_e32 v0, v16, v124
	v_fma_f32 v0, v56, v125, -v0
	v_cvt_pk_bf16_f32 v0, v0, s0
	global_store_short v[118:119], v0, off offset:384
	v_mul_f32_e32 v0, v17, v123
	v_fma_f32 v0, v57, v122, -v0
	v_cvt_pk_bf16_f32 v0, v0, s0
	global_store_short v[120:121], v0, off offset:384
	v_mul_f32_e32 v0, v10, v128
	v_fma_f32 v0, v46, v129, -v0
	v_cvt_pk_bf16_f32 v0, v0, s0
	global_store_short v[114:115], v0, off offset:416
	v_mul_f32_e32 v0, v11, v126
	v_fma_f32 v0, v47, v127, -v0
	v_cvt_pk_bf16_f32 v0, v0, s0
	global_store_short v[116:117], v0, off offset:416
	v_mul_f32_e32 v0, v12, v124
	v_fma_f32 v0, v48, v125, -v0
	v_cvt_pk_bf16_f32 v0, v0, s0
	global_store_short v[118:119], v0, off offset:416
	v_mul_f32_e32 v0, v13, v123
	v_fma_f32 v0, v49, v122, -v0
	v_cvt_pk_bf16_f32 v0, v0, s0
	global_store_short v[120:121], v0, off offset:416
	v_mul_f32_e32 v0, v6, v128
	v_fma_f32 v0, v38, v129, -v0
	v_cvt_pk_bf16_f32 v0, v0, s0
	global_store_short v[114:115], v0, off offset:448
	v_mul_f32_e32 v0, v7, v126
	v_fma_f32 v0, v39, v127, -v0
	v_cvt_pk_bf16_f32 v0, v0, s0
	global_store_short v[116:117], v0, off offset:448
	v_mul_f32_e32 v0, v8, v124
	v_fma_f32 v0, v40, v125, -v0
	v_cvt_pk_bf16_f32 v0, v0, s0
	global_store_short v[118:119], v0, off offset:448
	v_mul_f32_e32 v0, v9, v123
	v_fma_f32 v0, v41, v122, -v0
	v_cvt_pk_bf16_f32 v0, v0, s0
	global_store_short v[120:121], v0, off offset:448
	v_mul_f32_e32 v0, v2, v128
	v_fma_f32 v0, v30, v129, -v0
	v_cvt_pk_bf16_f32 v0, v0, s0
	global_store_short v[114:115], v0, off offset:480
	v_mul_f32_e32 v0, v3, v126
	v_fma_f32 v0, v31, v127, -v0
	v_cvt_pk_bf16_f32 v0, v0, s0
	global_store_short v[116:117], v0, off offset:480
	v_mul_f32_e32 v0, v4, v124
	v_fma_f32 v0, v32, v125, -v0
	v_cvt_pk_bf16_f32 v0, v0, s0
	global_store_short v[118:119], v0, off offset:480
	v_mul_f32_e32 v0, v5, v123
	v_fma_f32 v0, v33, v122, -v0
	v_cvt_pk_bf16_f32 v0, v0, s0
	global_store_short v[120:121], v0, off offset:480
	s_branch .LBB0_381
